# GEMM1 ragged 12th round overlapped with P2: workgroups 0..63 pass seam 1 before their 12th tile, P2 items rebalanced 5/8/7 per workgroup (static), flag-line seams
# baseline (speedup 1.0000x reference)
; __global__ void __launch_bounds__(512, 2) hybrid_fwd(Args a) {
;     ...
;         if (a.n_fp8 > 0) {
;             pg8::Gemm g{(const bf16_t*)XB8, WinT, D / 2, D}; pg8::OrderList S{M / 256, a.n_fp8, (M / 256) * a.n_fp8, G, bx, D / 128, a.tl_fp8};
;             Epi1 E{H, csA, csB, a.b_gate, 0, 1.0f / W8_SCALE};
;             pg8::gemm_phase<Epi1, pg8::OrderList, true>(lds, g, S, E);
.LBB0_62:
	s_or_b64 exec, exec, s[4:5]
	s_load_dword s46, s[70:71], 0x1c4
	s_add_u32 s96, s90, 0x9000000
	s_addc_u32 s97, s91, 0
	s_barrier
	s_waitcnt lgkmcnt(0)
	s_mov_b32 s101, 0
	s_cmp_lg_u32 s92, 0x100
	s_cbranch_scc1 .Lrag_off
	s_cmp_lg_u32 s46, 45
	s_cbranch_scc1 .Lrag_off
	s_mov_b32 s101, 1
.Lrag_off:
	s_cmp_lt_i32 s46, 1
	s_cbranch_scc1 .LBB0_267
	s_lshl_b32 s16, s46, 6
	s_cmp_lt_i32 s2, s16
	s_cselect_b64 s[4:5], -1, 0
	s_cmp_ge_i32 s2, s16
	v_readfirstlane_b32 s24, v160
	s_cbranch_scc1 .LBB0_65
	s_lshl_b32 s7, s46, 1
	s_abs_i32 s8, s7
	v_cvt_f32_u32_e32 v0, s8
	s_lshr_b32 s1, s3, 29
	s_add_i32 s1, s2, s1
	s_and_b32 s6, s1, -8
	v_rcp_iflag_f32_e32 v0, v0
	s_lshl_b32 s0, s46, 3
	s_sub_i32 s6, s2, s6
	s_and_b32 s0, s0, 0x1ffffff8
	v_mul_f32_e32 v0, 0x4f7ffffe, v0
	v_cvt_u32_f32_e32 v0, v0
	s_lshr_b32 s9, s6, 31
	s_or_b32 s0, s0, s9
	s_sub_i32 s9, 0, s8
	v_readfirstlane_b32 s10, v0
	s_mul_i32 s0, s0, s6
	s_ashr_i32 s1, s1, 3
	s_mul_i32 s9, s9, s10
	s_add_i32 s0, s0, s1
	s_mul_hi_u32 s9, s10, s9
	s_abs_i32 s6, s0
	s_add_i32 s10, s10, s9
	s_mul_hi_u32 s9, s6, s10
	s_mul_i32 s10, s9, s8
	s_xor_b32 s1, s0, s7
	s_sub_i32 s6, s6, s10
	s_ashr_i32 s1, s1, 31
	s_add_i32 s10, s9, 1
	s_sub_i32 s11, s6, s8
	s_cmp_ge_u32 s6, s8
	s_cselect_b32 s9, s10, s9
	s_cselect_b32 s6, s11, s6
	s_add_i32 s10, s9, 1
	s_cmp_ge_u32 s6, s8
	s_cselect_b32 s6, s10, s9
	s_xor_b32 s6, s6, s1
	s_sub_i32 s1, s6, s1
	s_lshl_b32 s6, s1, 1
	s_sub_i32 s8, 64, s6
	s_min_i32 s8, s8, 2
	s_abs_i32 s9, s8
	v_cvt_f32_u32_e32 v0, s9
	s_sub_i32 s10, 0, s9
	s_mul_i32 s1, s1, s7
	s_sub_i32 s0, s0, s1
	v_rcp_iflag_f32_e32 v0, v0
	s_abs_i32 s7, s0
	s_xor_b32 s1, s0, s8
	s_ashr_i32 s1, s1, 31
	v_mul_f32_e32 v0, 0x4f7ffffe, v0
	v_cvt_u32_f32_e32 v0, v0
	s_nop 0
	v_readfirstlane_b32 s11, v0
	s_mul_i32 s10, s10, s11
	s_mul_hi_u32 s10, s11, s10
	s_add_i32 s11, s11, s10
	s_mul_hi_u32 s10, s7, s11
	s_mul_i32 s11, s10, s9
	s_sub_i32 s7, s7, s11
	s_add_i32 s11, s10, 1
	s_sub_i32 s17, s7, s9
	s_cmp_ge_u32 s7, s9
	s_cselect_b32 s10, s11, s10
	s_cselect_b32 s7, s17, s7
	s_add_i32 s11, s10, 1
	s_cmp_ge_u32 s7, s9
	s_cselect_b32 s7, s11, s10
	s_xor_b32 s7, s7, s1
	s_sub_i32 s1, s7, s1
	s_mul_i32 s7, s1, s8
	s_sub_i32 s0, s0, s7
	s_add_i32 s8, s0, s6
	s_ashr_i32 s6, s1, 31
	s_add_u32 s0, s70, s1
	s_addc_u32 s1, s71, s6
	v_mov_b32_e32 v0, 0
	global_load_ubyte v0, v0, s[0:1] offset:400
	s_waitcnt vmcnt(0)
	v_readfirstlane_b32 s0, v0

; __device__ __forceinline__ void own_barrier(unsigned* cnt, unsigned G) {
;     asm volatile("s_waitcnt vmcnt(0) lgkmcnt(0)" ::: "memory");
;     __syncthreads();
;     if (threadIdx.x == 0) {
;         __builtin_amdgcn_fence(__ATOMIC_RELEASE, "agent"); asm volatile("s_waitcnt vmcnt(0)" ::: "memory");
;         unsigned target;
;         if ((G & 7u) == 0u) { target = 8u;
;             const unsigned old = __hip_atomic_fetch_add(cnt + 64 * (1 + (blockIdx.x & 7)), 1u, __ATOMIC_RELAXED, __HIP_MEMORY_SCOPE_AGENT);
;             if (old + 1u == (G >> 3)) __hip_atomic_fetch_add(cnt, 1u, __ATOMIC_RELAXED, __HIP_MEMORY_SCOPE_AGENT); }
;         else { target = G; __hip_atomic_fetch_add(cnt, 1u, __ATOMIC_RELAXED, __HIP_MEMORY_SCOPE_AGENT); }
;         unsigned spins = 0;
;         while (__hip_atomic_load(cnt, __ATOMIC_RELAXED, __HIP_MEMORY_SCOPE_AGENT) < target && ++spins < (1u << 22)) __builtin_amdgcn_s_sleep(1);
;         __builtin_amdgcn_fence(__ATOMIC_ACQUIRE, "agent"); asm volatile("s_waitcnt vmcnt(0)" ::: "memory");
;     }
;     __syncthreads();
.LBB0_220:
	s_cmp_lg_u32 s101, 1
	s_cbranch_scc1 .Lmid_skip
	s_cmp_lg_u32 s67, 11
	s_cbranch_scc1 .Lmid_skip
	s_waitcnt vmcnt(0) lgkmcnt(0)
	s_barrier
	v_readfirstlane_b32 s100, v160
	s_cmp_lg_u32 s100, 0
	s_cbranch_scc1 .Lmid_join
	s_mov_b64 exec, 1
	buffer_wbl2 sc1
	s_waitcnt vmcnt(0)
	v_mov_b32_e32 v245, 0x8e01000
	v_mov_b32_e32 v244, 1
	global_atomic_add v244, v245, v244, s[90:91] sc0
	s_lshl_b32 s100, s2, 12
	s_add_u32 s100, s100, 0x8e10000
	v_mov_b32_e32 v245, s100
	s_waitcnt vmcnt(0)
	v_readfirstlane_b32 s100, v244
	s_cmp_eq_u32 s100, 0xff
	s_cbranch_scc0 .Lmid_wait
	s_mov_b64 exec, -1
	v_mbcnt_lo_u32_b32 v243, -1, 0
	v_mbcnt_hi_u32_b32 v243, -1, v243
	v_lshlrev_b32_e32 v243, 12, v243
	v_add_u32_e32 v243, 0x8e10000, v243
	v_mov_b32_e32 v244, 1
	global_store_dword v243, v244, s[90:91] sc1
	v_add_u32_e32 v243, 0x40000, v243
	global_store_dword v243, v244, s[90:91] sc1
	v_add_u32_e32 v243, 0x40000, v243
	global_store_dword v243, v244, s[90:91] sc1
	v_add_u32_e32 v243, 0x40000, v243
	global_store_dword v243, v244, s[90:91] sc1
	s_mov_b64 exec, 1
	s_branch .Lmid_done

; __device__ __forceinline__ void own_barrier(unsigned* cnt, unsigned G) {
;     ...
;         while (__hip_atomic_load(cnt, __ATOMIC_RELAXED, __HIP_MEMORY_SCOPE_AGENT) < target && ++spins < (1u << 22)) __builtin_amdgcn_s_sleep(1);
;         __builtin_amdgcn_fence(__ATOMIC_ACQUIRE, "agent"); asm volatile("s_waitcnt vmcnt(0)" ::: "memory");
;     }
;     __syncthreads();
.Lmid_poll:
	global_load_dword v244, v245, s[90:91] sc1
	s_waitcnt vmcnt(0)
	v_cmp_eq_u32_e32 vcc, 1, v244
	s_cbranch_vccnz .Lmid_done
	s_sleep 1
	s_add_i32 s100, s100, -1
	s_cmp_lg_u32 s100, 0
	s_cbranch_scc1 .Lmid_poll
.Lmid_done:
	buffer_inv sc1
	s_waitcnt vmcnt(0)
	s_mov_b64 exec, -1
.Lmid_join:
	s_barrier

; __device__ __forceinline__ void own_barrier(unsigned* cnt, unsigned G) {
;     asm volatile("s_waitcnt vmcnt(0) lgkmcnt(0)" ::: "memory");
;     __syncthreads();
;     if (threadIdx.x == 0) {
;         __builtin_amdgcn_fence(__ATOMIC_RELEASE, "agent"); asm volatile("s_waitcnt vmcnt(0)" ::: "memory");
;         unsigned target;
;         if ((G & 7u) == 0u) { target = 8u;
;             const unsigned old = __hip_atomic_fetch_add(cnt + 64 * (1 + (blockIdx.x & 7)), 1u, __ATOMIC_RELAXED, __HIP_MEMORY_SCOPE_AGENT);
;             if (old + 1u == (G >> 3)) __hip_atomic_fetch_add(cnt, 1u, __ATOMIC_RELAXED, __HIP_MEMORY_SCOPE_AGENT); }
;         else { target = G; __hip_atomic_fetch_add(cnt, 1u, __ATOMIC_RELAXED, __HIP_MEMORY_SCOPE_AGENT); }
.LBB0_279:
	s_waitcnt vmcnt(0) lgkmcnt(0)
	v_cmp_eq_u32_e64 s[0:1], 0, v160
	v_cmp_ne_u32_e32 vcc, 0, v160
	s_waitcnt vmcnt(0)
	v_writelane_b32 v242, s0, 4
	s_barrier
	s_nop 0
	v_writelane_b32 v242, s1, 5
	s_and_saveexec_b64 s[0:1], vcc
	s_xor_b64 s[0:1], exec, s[0:1]
	s_and_b32 s4, s92, 7
	s_or_saveexec_b64 s[0:1], s[0:1]
	v_mov_b32_e32 v0, s4
	s_xor_b64 exec, exec, s[0:1]
	s_cbranch_execz .LBB0_301
	s_cmp_lg_u32 s101, 1
	s_cbranch_scc1 .Lseam1_go
	s_cmp_lt_u32 s2, 64
	s_cbranch_scc0 .Lseam1_go
	s_and_b32 s12, s92, 7
	s_branch .Lseam1_join
.Lseam1_go:
	s_cmp_lg_u32 s92, 0x100
	s_cbranch_scc1 .Lseam1_orig
	buffer_wbl2 sc1
	s_waitcnt vmcnt(0)
	v_mov_b32_e32 v1, 0x8e01000
	v_mov_b32_e32 v2, 1
	global_atomic_add v2, v1, v2, s[90:91] sc0
	s_lshl_b32 s100, s2, 12
	s_add_u32 s100, s100, 0x8e10000
	v_mov_b32_e32 v1, s100
	s_waitcnt vmcnt(0)
	v_readfirstlane_b32 s100, v2
	s_cmp_eq_u32 s100, 0xff
	s_cbranch_scc0 .Lseam1_wait
	s_mov_b64 exec, -1
	v_mbcnt_lo_u32_b32 v243, -1, 0
	v_mbcnt_hi_u32_b32 v243, -1, v243
	v_lshlrev_b32_e32 v243, 12, v243
	v_add_u32_e32 v243, 0x8e10000, v243
	v_mov_b32_e32 v244, 1
	global_store_dword v243, v244, s[90:91] sc1
	v_add_u32_e32 v243, 0x40000, v243
	global_store_dword v243, v244, s[90:91] sc1
	v_add_u32_e32 v243, 0x40000, v243
	global_store_dword v243, v244, s[90:91] sc1
	v_add_u32_e32 v243, 0x40000, v243
	global_store_dword v243, v244, s[90:91] sc1
	s_mov_b64 exec, 1
	s_branch .Lseam1_done

; __global__ void __launch_bounds__(512, 2) hybrid_fwd(Args a) {
;     ...
;         for (int i0 = bx; i0 < N_A + N_B; i0 += G) {
;             int it = i0;
;             if (xmap) { const int k = i0 / G;
;                 if (i0 < N_A) it = xcd * (N_A / 8) + k * perx + jx;
;                 else { const int kb = (i0 - N_A) / G; it = N_A + xcd * (N_B / 8) + kb * perx + jx; } }
.LBB0_303:
	s_or_b64 exec, exec, s[14:15]
	s_add_i32 s22, s22, s92
	s_cmp_eq_u32 s101, 1
	s_cbranch_scc0 .Lp2_latch_orig
	s_cmp_lt_u32 s2, 64
	s_cbranch_scc0 .Lp2_notlate
	s_cmpk_lt_i32 s22, 0x500
	s_cbranch_scc1 .LBB0_304
	s_branch .LBB0_339
.Lp2_notlate:
	s_cmpk_lt_i32 s22, 0x700
	s_cbranch_scc1 .LBB0_304
	s_cmp_lt_u32 s2, 0xc0
	s_cbranch_scc0 .LBB0_339
	s_cmp_lt_u32 s22, 0x1000
	s_cbranch_scc0 .LBB0_339
	s_mov_b32 s22, 0x1000
	s_branch .LBB0_304
.Lp2_latch_orig:
	s_cmpk_lt_i32 s22, 0x700
	s_cbranch_scc0 .LBB0_339

; #define LAS __attribute__((address_space(3)))
; __global__ void __launch_bounds__(512, 2) hybrid_fwd(Args a) {
;     ...
;         for (int i0 = bx; i0 < N_A + N_B; i0 += G) {
;             int it = i0;
;             if (xmap) { const int k = i0 / G;
;                 if (i0 < N_A) it = xcd * (N_A / 8) + k * perx + jx;
;                 else { const int kb = (i0 - N_A) / G; it = N_A + xcd * (N_B / 8) + kb * perx + jx; } }
;     ...
;                 const int bi = it - N_A, grp = bi >> 9, rem = bi & 511, hs = rem >> 7, rb = rem & 127;
;                 const int dsh = 2 * grp, d = 1 << dsh;
;                 const int nblk = 128 >> dsh, r = rb / nblk, b = rb % nblk;
;                 LAS unsigned char* Kl = lds; LAS unsigned char* Vl = lds + 256 * 288;
;                 const int jlo = (b == 0) ? 128 : 0;
;                 const int colh = grp * 512 + hs * 128;
;                 load_kv<128>(Kl, Vl, H + OFF_KB + colh, H + OFF_VB + colh, ((long)(b - 1) * 128) * d + r, d, jlo, tid);
.LBB0_309:
	v_readlane_b32 s16, v242, 9
	s_add_i32 s16, s23, s16
	s_nop 0
	v_mov_b32_e32 v1, s16
	s_cmp_lt_u32 s22, 0x1000
	s_cbranch_scc1 .Lp2_noextra
	s_sub_u32 s16, s2, 64
	s_lshr_b32 s17, s16, 6
	s_add_u32 s17, s17, 4
	s_lshl_b32 s17, s17, 5
	s_and_b32 s16, s16, 63
	s_lshr_b32 s16, s16, 3
	s_add_u32 s16, s16, s17
	s_and_b32 s17, s2, 7
	s_mul_i32 s17, s17, 0xc0
	s_add_u32 s16, s16, s17
	s_add_u32 s16, s16, 0x100
	v_mov_b32_e32 v1, s16
.Lp2_noextra:
.LBB0_310:
	s_or_b64 exec, exec, s[14:15]
	s_movk_i32 s14, 0xff
	v_cmp_lt_i32_e32 vcc, s14, v1
	s_barrier
	s_and_saveexec_b64 s[14:15], vcc
	s_xor_b64 s[86:87], exec, s[14:15]
	s_cbranch_execz .LBB0_328
	v_add_u32_e32 v2, 0xffffff00, v1
	v_lshrrev_b32_e32 v148, 9, v2
	v_lshlrev_b32_e32 v147, 1, v148
	s_movk_i32 s14, 0x80
	v_and_b32_e32 v0, 0x7f, v1
	v_lshrrev_b32_e64 v3, v147, s14
	v_sub_u32_e32 v4, 7, v147
	v_lshrrev_b32_e32 v154, v4, v0
	v_add_u32_e32 v0, -1, v3
	s_movk_i32 s14, 0x7f
	v_bitop3_b32 v149, v0, v1, s14 bitop3:0x80
	v_bfe_u32 v222, v2, 7, 2
	v_subrev_co_u32_e32 v0, vcc, 1, v149
	v_lshlrev_b32_e32 v150, 7, v222
	s_movk_i32 s14, 0xfe00
	v_ashrrev_i32_e32 v1, 31, v0
	v_and_or_b32 v152, v2, s14, v150
	v_mov_b32_e32 v153, v8
	v_lshlrev_b64 v[0:1], 7, v[0:1]
	v_mov_b32_e32 v96, 0
	v_cndmask_b32_e32 v223, 0, v219, vcc
	v_lshlrev_b64 v[2:3], 1, v[152:153]
	v_lshlrev_b64 v[166:167], v147, v[0:1]
	v_lshl_add_u64 v[158:159], s[4:5], 0, v[2:3]
	v_lshl_add_u64 v[164:165], s[8:9], 0, v[2:3]
	v_or_b32_e32 v166, v166, v154
	v_cmp_ge_u32_e32 vcc, v112, v223
	v_mov_b32_e32 v97, v96
	v_mov_b32_e32 v98, v96
	v_mov_b32_e32 v99, v96
	v_mov_b32_e32 v0, v96
	v_mov_b32_e32 v1, v96
	v_mov_b32_e32 v2, v96
	v_mov_b32_e32 v3, v96
	s_and_saveexec_b64 s[14:15], vcc
	s_cbranch_execz .LBB0_313
	v_lshlrev_b64 v[0:1], v147, v[112:113]
	v_lshl_add_u64 v[0:1], v[166:167], 0, v[0:1]
	v_mad_u64_u32 v[2:3], s[16:17], v0, s19, 0
	v_mov_b32_e32 v0, v3
	v_mad_u64_u32 v[0:1], s[16:17], v1, s19, v[0:1]
	v_or_b32_e32 v2, v2, v110
	v_mov_b32_e32 v3, v0
	v_lshlrev_b64 v[0:1], 1, v[2:3]
	v_lshl_add_u64 v[2:3], v[158:159], 0, v[0:1]
	v_lshl_add_u64 v[4:5], v[164:165], 0, v[0:1]
	global_load_dwordx4 v[0:3], v[2:3], off
	s_nop 0
	global_load_dwordx4 v[96:99], v[4:5], off
